# attention K/V prefetch addresses updated incrementally (7 VALU per key tile instead of 52 + 6 nops)
# speedup vs baseline: 1.0240x; 1.0075x over previous
; DEV void attn_tile(const Params& p, int l, int tile, char* smem, bool do_store = true) {
;     ...
;   auto gload = [&](int kt) {
;     const int k0 = kt * 128;
; #pragma unroll
;     for (int i = 0; i < 4; ++i) {
;       const int kidx = k0 + kr0 + 32 * i;
;       const int krow = kidx < CTXL ? T_LAT + b * CTXL + kidx : b * SEQ + kidx - CTXL;
;       kreg[i] = *(const u32x4*)(ZK + (size_t)krow * 512 + head * 128 + kch * 8);
;       vreg[i] = *(const u32x4*)(vtb + (size_t)(vr0 + 32 * i) * TK + k0 + vch * 8);
;     }
;   };
;     ...
;     if (kt + 1 < nkt) gload(kt + 1);
.LBB0_600:
	s_cmp_lg_u32 s0, 0
	s_cbranch_scc1 .Latt_a3_inc
	v_add_u32_e32 v66, s31, v200
	v_add_u32_e32 v64, 0x80, v66
	s_movk_i32 s38, 0x100
	v_cmp_gt_i32_e32 vcc, s38, v64
	s_mov_b32 s37, 0x44000
	s_and_b32 s1, s0, 1
	v_cndmask_b32_e64 v65, 12, 8, vcc
	v_cndmask_b32_e32 v67, v236, v237, vcc
	v_lshlrev_b32_e64 v65, v65, s30
	v_add3_u32 v64, v67, v65, v64
	v_ashrrev_i32_e32 v65, 31, v64
	v_lshlrev_b64 v[64:65], 10, v[64:65]
	v_lshl_add_u64 v[64:65], v[184:185], 0, v[64:65]
	global_load_dwordx4 v[114:117], v[64:65], off
	v_mov_b32_e32 v220, v64
	v_mov_b32_e32 v221, v65
	global_load_dwordx4 v[118:121], v[186:187], off
	v_add_u32_e32 v64, 0xa0, v66
	v_cmp_gt_i32_e32 vcc, s38, v64
	s_nop 1
	v_cndmask_b32_e64 v65, 12, 8, vcc
	v_cndmask_b32_e32 v67, v236, v237, vcc
	v_lshlrev_b32_e64 v65, v65, s30
	v_add3_u32 v64, v67, v65, v64
	v_ashrrev_i32_e32 v65, 31, v64
	v_lshlrev_b64 v[64:65], 10, v[64:65]
	v_lshl_add_u64 v[64:65], v[184:185], 0, v[64:65]
	global_load_dwordx4 v[122:125], v[64:65], off
	v_mov_b32_e32 v222, v64
	v_mov_b32_e32 v223, v65
	v_add_co_u32_e32 v64, vcc, s37, v186
	s_mov_b32 s37, 0x88000
	s_nop 0
	v_addc_co_u32_e32 v65, vcc, 0, v187, vcc
	global_load_dwordx4 v[126:129], v[64:65], off
	v_mov_b32_e32 v230, v64
	v_mov_b32_e32 v231, v65
	v_add_u32_e32 v64, 0xc0, v66
	v_cmp_gt_i32_e32 vcc, s38, v64
	s_nop 1
	v_cndmask_b32_e64 v65, 12, 8, vcc
	v_cndmask_b32_e32 v67, v236, v237, vcc
	v_lshlrev_b32_e64 v65, v65, s30
	v_add3_u32 v64, v67, v65, v64
	v_ashrrev_i32_e32 v65, 31, v64
	v_lshlrev_b64 v[64:65], 10, v[64:65]
	v_lshl_add_u64 v[64:65], v[184:185], 0, v[64:65]
	global_load_dwordx4 v[130:133], v[64:65], off
	v_mov_b32_e32 v224, v64
	v_mov_b32_e32 v225, v65
	v_add_co_u32_e32 v64, vcc, s37, v186
	s_mov_b32 s37, 0xcc000
	s_nop 0
	v_addc_co_u32_e32 v65, vcc, 0, v187, vcc
	global_load_dwordx4 v[134:137], v[64:65], off
	v_mov_b32_e32 v238, v64
	v_mov_b32_e32 v239, v65
	v_add_u32_e32 v64, 0xe0, v66
	v_cmp_gt_i32_e32 vcc, s38, v64
	s_nop 1
	v_cndmask_b32_e64 v65, 12, 8, vcc
	v_cndmask_b32_e32 v66, v236, v237, vcc
	v_lshlrev_b32_e64 v65, v65, s30
	v_add3_u32 v64, v66, v65, v64
	v_ashrrev_i32_e32 v65, 31, v64
	v_lshlrev_b64 v[64:65], 10, v[64:65]
	v_lshl_add_u64 v[64:65], v[184:185], 0, v[64:65]
	global_load_dwordx4 v[138:141], v[64:65], off
	v_mov_b32_e32 v228, v64
	v_mov_b32_e32 v229, v65
	v_add_co_u32_e32 v64, vcc, s37, v186
	s_mul_i32 s37, s1, 0x11000
	s_nop 0
	v_addc_co_u32_e32 v65, vcc, 0, v187, vcc
	s_add_i32 s37, s37, 0
	global_load_dwordx4 v[142:145], v[64:65], off
	v_mov_b32_e32 v242, v64
	v_mov_b32_e32 v243, v65
	s_branch .Latt_a3_join
.Latt_a3_inc:
	s_and_b32 s1, s0, 1
	s_mov_b32 s100, 0x20000
	s_mov_b32 s101, 0
	s_cmp_lg_u32 s0, 1
	s_cbranch_scc1 .Latt_a3_nd
	s_mul_i32 s100, s30, 0xf00
	s_sub_u32 s100, s100, 0x8080
	s_lshl_b32 s100, s100, 10
	s_mov_b32 s101, -1
.Latt_a3_nd:
	s_mov_b64 s[38:39], 0x100
	v_lshl_add_u64 v[220:221], v[220:221], 0, s[100:101]
	v_lshl_add_u64 v[222:223], v[222:223], 0, s[100:101]
	v_lshl_add_u64 v[224:225], v[224:225], 0, s[100:101]
	v_lshl_add_u64 v[228:229], v[228:229], 0, s[100:101]
	v_lshl_add_u64 v[230:231], v[230:231], 0, s[38:39]
	v_lshl_add_u64 v[238:239], v[238:239], 0, s[38:39]
	v_lshl_add_u64 v[242:243], v[242:243], 0, s[38:39]
	global_load_dwordx4 v[114:117], v[220:221], off
	global_load_dwordx4 v[118:121], v[186:187], off
	global_load_dwordx4 v[122:125], v[222:223], off
	global_load_dwordx4 v[126:129], v[230:231], off
	global_load_dwordx4 v[130:133], v[224:225], off
	global_load_dwordx4 v[134:137], v[238:239], off
	global_load_dwordx4 v[138:141], v[228:229], off
	global_load_dwordx4 v[142:145], v[242:243], off
	s_mul_i32 s37, s1, 0x11000
; DEV void attn_tile(const Params& p, int l, int tile, char* smem, bool do_store = true) {
;     ...
;     const char* Ks = smem + cur * ATT2_ST;
;     const char* Vs = Ks + 128 * KROW;
; #pragma unroll
;     for (int h2 = 0; h2 < 2; ++h2) {
;     const char* kp = Ks + (h2 * 64 + kos) * KROW + (map * 64 + hh * 8) * 2;
;     const char* vp = Vs + ql * KROW + hh * 16 + h2 * 128;
;     bf16x8 kf0[4], kf1[4];
; #pragma unroll
;     for (int ks = 0; ks < 4; ++ks) { kf0[ks] = *(const bf16x8*)(kp + ks * 32); kf1[ks] = *(const bf16x8*)(kp + 32 * KROW + ks * 32); }
;     f32x16 s0, s1;
; #pragma unroll
;     for (int e = 0; e < 16; ++e) { s0[e] = 0.f; s1[e] = 0.f; }
; #pragma unroll
;     for (int ks = 0; ks < 4; ++ks) s0 = __builtin_amdgcn_mfma_f32_32x32x16_bf16(kf0[ks], qf[ks], s0, 0, 0, 0);
; #pragma unroll
;     for (int ks = 0; ks < 4; ++ks) s1 = __builtin_amdgcn_mfma_f32_32x32x16_bf16(kf1[ks], qf[ks], s1, 0, 0, 0);
;     bf16x8 vf[8];
; #pragma unroll
;     for (int dt = 0; dt < 4; ++dt)
; #pragma unroll
;       for (int k2 = 0; k2 < 2; ++k2) vf[dt * 2 + k2] = *(const bf16x8*)(vp + dt * 32 * KROW + (k2 * 16) * 2);
;     float mx = fmaxf(s0[0], s1[0]);
; #pragma unroll
;     for (int e = 1; e < 16; ++e) mx = fmaxf(mx, fmaxf(s0[e], s1[e]));
;     mx = xor32_max(mx);
;     const float mnew = (mx > m + 8.f) ? mx : m;
;     if (__any(mnew > m)) {
;       const float alpha = __builtin_amdgcn_exp2f(m - mnew);
;       lsum *= alpha;
; #pragma unroll
;       for (int dt = 0; dt < 4; ++dt)
; #pragma unroll
;         for (int e = 0; e < 16; ++e) o[dt][e] *= alpha;
;     }
;     m = mnew;
.Latt_a3_join:
	v_add_u32_e32 v64, s37, v204
	v_add_u32_e32 v65, s37, v201
	v_add_u32_e32 v210, v64, v203
	v_add_u32_e32 v205, v65, v96
	ds_read_b128 v[64:67], v210 offset:8704
	ds_read_b128 v[68:71], v210
	ds_read_b128 v[72:75], v210 offset:32
	ds_read_b128 v[212:215], v210 offset:8736
	ds_read_b128 v[76:79], v210 offset:64
	ds_read_b128 v[216:219], v210 offset:8768
	ds_read_b128 v[146:149], v210 offset:96
	ds_read_b128 v[178:181], v210 offset:8800
	s_waitcnt lgkmcnt(6)
	v_mfma_f32_32x32x16_bf16 v[80:95], v[68:71], v[110:113], 0
	s_waitcnt lgkmcnt(5)
	v_mfma_f32_32x32x16_bf16 v[80:95], v[72:75], v[106:109], v[80:95]
	s_waitcnt lgkmcnt(3)
	v_mfma_f32_32x32x16_bf16 v[80:95], v[76:79], v[102:105], v[80:95]
	v_mfma_f32_32x32x16_bf16 v[64:79], v[64:67], v[110:113], 0
	v_mfma_f32_32x32x16_bf16 v[64:79], v[212:215], v[106:109], v[64:79]
	s_waitcnt lgkmcnt(2)
	v_mfma_f32_32x32x16_bf16 v[64:79], v[216:219], v[102:105], v[64:79]
	s_waitcnt lgkmcnt(1)
	v_mfma_f32_32x32x16_bf16 v[80:95], v[146:149], v[98:101], v[80:95]
	ds_read_b128 v[174:177], v205 offset:34816
	ds_read_b128 v[170:173], v205 offset:34848
	ds_read_b128 v[166:169], v205 offset:43520
	ds_read_b128 v[162:165], v205 offset:43552
	ds_read_b128 v[146:149], v205 offset:52224
	ds_read_b128 v[150:153], v205 offset:52256
	ds_read_b128 v[154:157], v205 offset:60928
	ds_read_b128 v[158:161], v205 offset:60960
	s_waitcnt lgkmcnt(8)
	v_mfma_f32_32x32x16_bf16 v[64:79], v[178:181], v[98:101], v[64:79]
	s_nop 1
	v_max3_f32 v178, v80, v81, v82
	v_max3_f32 v179, v83, v84, v85
	v_max3_f32 v180, v86, v87, v88
	v_max3_f32 v181, v89, v90, v91
	v_max3_f32 v178, v178, v92, v93
	v_max3_f32 v179, v179, v94, v95
	s_nop 3
	v_max3_f32 v180, v180, v64, v65
	v_max3_f32 v181, v181, v66, v67
	v_max3_f32 v178, v178, v68, v69
	v_max3_f32 v179, v179, v70, v71
	v_max3_f32 v180, v180, v72, v73
	v_max3_f32 v181, v181, v74, v75
	v_max3_f32 v178, v178, v76, v77
	v_max3_f32 v179, v179, v78, v79
	v_max3_f32 v178, v178, v179, v180
	v_max_f32_e32 v178, v178, v181
	v_mov_b32_e32 v179, v178
	s_nop 1
	v_permlane32_swap_b32_e32 v178, v179
	v_max_f32_e32 v178, v178, v179
	v_add_f32_e32 v179, 0x41000000, v208
	v_cmp_gt_f32_e32 vcc, v178, v179
	s_nop 1
	v_cndmask_b32_e32 v211, v208, v178, vcc
	v_cmp_gt_f32_e32 vcc, v211, v208
	s_cbranch_vccz .LBB0_602
	v_sub_f32_e32 v178, v208, v211
	v_exp_f32_e32 v178, v178
	s_nop 0
	v_pk_mul_f32 v[62:63], v[62:63], v[178:179] op_sel_hi:[1,0]
	v_pk_mul_f32 v[60:61], v[60:61], v[178:179] op_sel_hi:[1,0]
	v_pk_mul_f32 v[58:59], v[58:59], v[178:179] op_sel_hi:[1,0]
	v_pk_mul_f32 v[56:57], v[56:57], v[178:179] op_sel_hi:[1,0]
	v_pk_mul_f32 v[54:55], v[54:55], v[178:179] op_sel_hi:[1,0]
	v_pk_mul_f32 v[52:53], v[52:53], v[178:179] op_sel_hi:[1,0]
	v_pk_mul_f32 v[50:51], v[50:51], v[178:179] op_sel_hi:[1,0]
	v_pk_mul_f32 v[48:49], v[48:49], v[178:179] op_sel_hi:[1,0]
	v_pk_mul_f32 v[46:47], v[46:47], v[178:179] op_sel_hi:[1,0]
	v_pk_mul_f32 v[44:45], v[44:45], v[178:179] op_sel_hi:[1,0]
	v_pk_mul_f32 v[42:43], v[42:43], v[178:179] op_sel_hi:[1,0]
	v_pk_mul_f32 v[40:41], v[40:41], v[178:179] op_sel_hi:[1,0]
	v_pk_mul_f32 v[38:39], v[38:39], v[178:179] op_sel_hi:[1,0]
	v_pk_mul_f32 v[36:37], v[36:37], v[178:179] op_sel_hi:[1,0]
	v_pk_mul_f32 v[34:35], v[34:35], v[178:179] op_sel_hi:[1,0]
	v_pk_mul_f32 v[32:33], v[32:33], v[178:179] op_sel_hi:[1,0]
	v_pk_mul_f32 v[30:31], v[30:31], v[178:179] op_sel_hi:[1,0]
	v_pk_mul_f32 v[28:29], v[28:29], v[178:179] op_sel_hi:[1,0]
	v_pk_mul_f32 v[26:27], v[26:27], v[178:179] op_sel_hi:[1,0]
	v_pk_mul_f32 v[24:25], v[24:25], v[178:179] op_sel_hi:[1,0]
	v_pk_mul_f32 v[22:23], v[22:23], v[178:179] op_sel_hi:[1,0]
	v_pk_mul_f32 v[20:21], v[20:21], v[178:179] op_sel_hi:[1,0]
	v_pk_mul_f32 v[18:19], v[18:19], v[178:179] op_sel_hi:[1,0]
	v_pk_mul_f32 v[16:17], v[16:17], v[178:179] op_sel_hi:[1,0]
	v_pk_mul_f32 v[14:15], v[14:15], v[178:179] op_sel_hi:[1,0]
	v_pk_mul_f32 v[12:13], v[12:13], v[178:179] op_sel_hi:[1,0]
	v_pk_mul_f32 v[10:11], v[10:11], v[178:179] op_sel_hi:[1,0]
	v_pk_mul_f32 v[8:9], v[8:9], v[178:179] op_sel_hi:[1,0]
	v_pk_mul_f32 v[6:7], v[6:7], v[178:179] op_sel_hi:[1,0]
	v_pk_mul_f32 v[4:5], v[4:5], v[178:179] op_sel_hi:[1,0]
	v_pk_mul_f32 v[2:3], v[2:3], v[178:179] op_sel_hi:[1,0]
	v_pk_mul_f32 v[0:1], v[0:1], v[178:179] op_sel_hi:[1,0]
	v_mul_f32_e32 v209, v209, v178
